# nt hint on the SwiGLU hidden-buffer stores of P2 and P11 (keep the f32 residual stream in the memory-side cache)
# speedup vs baseline: 1.0069x; 1.0069x over previous
; __device__ __forceinline__ unsigned pk2(float lo, float hi) { const f32x2c v = {lo, hi}; const bf16x2c b = __builtin_convertvector(v, bf16x2c); return __builtin_bit_cast(unsigned, b); }
; __device__ __forceinline__ float silu_f(float x) { return x * fast_sigmoid(x); }
;     __device__ __forceinline__ void operator()(const f32x4 (&acc)[2][2][4][2], const pg8::Unit& u, int wr, int wc, int fr, int fq) const {
;         const int row0 = u.pm * 256 + wr * 64 + fr, col0 = u.pn * 128 + wc * 32 + 8 * fq;
; #pragma unroll
;         for (int ai = 0; ai < 2; ++ai)
; #pragma unroll
;             for (int m = 0; m < 4; ++m) {
;                 bf16_t* rowp = O + (size_t)(row0 + ai * 128 + m * 16) * ldc + col0;
;                 const f32x4 a0 = acc[ai][0][m][0], a1 = acc[ai][0][m][1], b0 = acc[ai][1][m][0], b1 = acc[ai][1][m][1];
;                 u32x4 w;
;                 w.x = pk2(silu_f(a0[0]) * b0[0], silu_f(a0[1]) * b0[1]); w.y = pk2(silu_f(a0[2]) * b0[2], silu_f(a0[3]) * b0[3]);
;                 w.z = pk2(silu_f(a1[0]) * b1[0], silu_f(a1[1]) * b1[1]); w.w = pk2(silu_f(a1[2]) * b1[2], silu_f(a1[3]) * b1[3]);
.LBB0_153:
	v_mul_f32_e32 v155, 0xbfb8aa3b, v124
	v_exp_f32_e32 v155, v155
	v_mul_f32_e32 v158, 0xbfb8aa3b, v125
	v_exp_f32_e32 v159, v158
	v_lshl_add_u32 v154, s28, 8, v148
	v_add_f32_e32 v155, 1.0, v155
	v_rcp_f32_e32 v158, v155
	v_add_f32_e32 v155, 1.0, v159
	v_mul_f32_e32 v159, 0xbfb8aa3b, v126
	v_exp_f32_e32 v160, v159
	v_mul_f32_e32 v159, 0xbfb8aa3b, v127
	v_exp_f32_e32 v161, v159
	v_rcp_f32_e32 v159, v155
	v_add_f32_e32 v155, 1.0, v160
	v_rcp_f32_e32 v160, v155
	v_add_f32_e32 v155, 1.0, v161
	v_rcp_f32_e32 v161, v155
	v_pk_mul_f32 v[124:125], v[124:125], v[158:159]
	v_lshl_add_u32 v144, s71, 7, v150
	v_pk_mul_f32 v[120:121], v[124:125], v[120:121]
	v_pk_mul_f32 v[124:125], v[126:127], v[160:161]
	v_cvt_pk_bf16_f32 v120, v120, v121
	v_mul_f32_e32 v121, 0xbfb8aa3b, v116
	v_pk_mul_f32 v[122:123], v[124:125], v[122:123]
	v_exp_f32_e32 v124, v121
	v_mul_f32_e32 v121, 0xbfb8aa3b, v117
	v_exp_f32_e32 v125, v121
	v_cvt_pk_bf16_f32 v121, v122, v123
	v_add_f32_e32 v122, 1.0, v124
	v_mul_f32_e32 v124, 0xbfb8aa3b, v118
	v_add_f32_e32 v123, 1.0, v125
	v_mul_f32_e32 v125, 0xbfb8aa3b, v119
	v_exp_f32_e32 v124, v124
	v_exp_f32_e32 v125, v125
	v_rcp_f32_e32 v122, v122
	v_rcp_f32_e32 v123, v123
	v_add_f32_e32 v124, 1.0, v124
	v_add_f32_e32 v125, 1.0, v125
	v_rcp_f32_e32 v124, v124
	v_rcp_f32_e32 v125, v125
	v_pk_mul_f32 v[116:117], v[116:117], v[122:123]
	v_ashrrev_i32_e32 v145, 31, v144
	v_pk_mul_f32 v[112:113], v[116:117], v[112:113]
	v_mul_f32_e32 v116, 0xbfb8aa3b, v110
	v_cvt_pk_bf16_f32 v122, v112, v113
	v_pk_mul_f32 v[112:113], v[118:119], v[124:125]
	v_mul_f32_e32 v117, 0xbfb8aa3b, v111
	v_pk_mul_f32 v[112:113], v[112:113], v[114:115]
	v_mul_f32_e32 v114, 0xbfb8aa3b, v108
	v_mul_f32_e32 v115, 0xbfb8aa3b, v109
	v_exp_f32_e32 v114, v114
	v_exp_f32_e32 v115, v115
	v_exp_f32_e32 v116, v116
	v_exp_f32_e32 v117, v117
	v_add_f32_e32 v114, 1.0, v114
	v_add_f32_e32 v115, 1.0, v115
	v_rcp_f32_e32 v114, v114
	v_rcp_f32_e32 v115, v115
	v_add_f32_e32 v116, 1.0, v116
	v_add_f32_e32 v117, 1.0, v117
	v_rcp_f32_e32 v116, v116
	v_rcp_f32_e32 v117, v117
	v_pk_mul_f32 v[108:109], v[108:109], v[114:115]
	s_cselect_b32 s98, 1, 0
	s_lshr_b32 s99, s28, 1
	s_and_b32 s100, s99, 7
	s_lshl_b32 s100, s100, 1
	s_bfe_u32 s101, s99, 0x10003
	s_or_b32 s100, s100, s101
	s_and_b32 s101, s99, 0x30
	s_or_b32 s100, s100, s101
	s_mul_i32 s100, s100, 0x300000
	s_mul_i32 s99, s99, 0x2c0000
	s_add_u32 s100, s100, 0xd000000
	s_sub_u32 s100, s100, s99
	s_add_u32 s100, s96, s100
	s_addc_u32 s101, s97, 0
	s_cmp_lg_u32 s98, 0
	v_mov_b64_e32 v[146:147], s[100:101]
	v_pk_mul_f32 v[104:105], v[108:109], v[104:105]
	v_pk_mul_f32 v[108:109], v[110:111], v[116:117]
	v_cvt_pk_bf16_f32 v104, v104, v105
	v_mul_f32_e32 v105, 0xbfb8aa3b, v100
	v_pk_mul_f32 v[106:107], v[108:109], v[106:107]
	v_exp_f32_e32 v108, v105
	v_mul_f32_e32 v105, 0xbfb8aa3b, v101
	v_exp_f32_e32 v109, v105
	v_cvt_pk_bf16_f32 v105, v106, v107
	v_add_f32_e32 v106, 1.0, v108
	v_mul_f32_e32 v108, 0xbfb8aa3b, v102
	v_add_f32_e32 v107, 1.0, v109
	v_mul_f32_e32 v109, 0xbfb8aa3b, v103
	v_exp_f32_e32 v108, v108
	v_exp_f32_e32 v109, v109
	v_rcp_f32_e32 v106, v106
	v_rcp_f32_e32 v107, v107
	v_add_f32_e32 v108, 1.0, v108
	v_add_f32_e32 v109, 1.0, v109
	v_rcp_f32_e32 v108, v108
	v_rcp_f32_e32 v109, v109
	v_pk_mul_f32 v[100:101], v[100:101], v[106:107]
	v_cvt_pk_bf16_f32 v123, v112, v113
	v_pk_mul_f32 v[96:97], v[100:101], v[96:97]
	v_mul_f32_e32 v100, 0xbfb8aa3b, v94
	v_cvt_pk_bf16_f32 v106, v96, v97
	v_pk_mul_f32 v[96:97], v[102:103], v[108:109]
	v_mul_f32_e32 v101, 0xbfb8aa3b, v95
	v_pk_mul_f32 v[96:97], v[96:97], v[98:99]
	v_mul_f32_e32 v98, 0xbfb8aa3b, v92
	v_mul_f32_e32 v99, 0xbfb8aa3b, v93
	v_exp_f32_e32 v98, v98
	v_exp_f32_e32 v99, v99
	v_exp_f32_e32 v100, v100
	v_exp_f32_e32 v101, v101
	v_add_f32_e32 v98, 1.0, v98
	v_add_f32_e32 v99, 1.0, v99
	v_rcp_f32_e32 v98, v98
	v_rcp_f32_e32 v99, v99
	v_add_f32_e32 v100, 1.0, v100
	v_add_f32_e32 v101, 1.0, v101
	v_rcp_f32_e32 v100, v100
	v_rcp_f32_e32 v101, v101
	v_pk_mul_f32 v[92:93], v[92:93], v[98:99]
	v_or_b32_e32 v112, 16, v154
	v_pk_mul_f32 v[88:89], v[92:93], v[88:89]
	v_pk_mul_f32 v[92:93], v[94:95], v[100:101]
	v_cvt_pk_bf16_f32 v88, v88, v89
	v_mul_f32_e32 v89, 0xbfb8aa3b, v84
	v_pk_mul_f32 v[90:91], v[92:93], v[90:91]
	v_exp_f32_e32 v92, v89
	v_mul_f32_e32 v89, 0xbfb8aa3b, v85
	v_exp_f32_e32 v93, v89
	v_cvt_pk_bf16_f32 v89, v90, v91
	v_add_f32_e32 v90, 1.0, v92
	v_mul_f32_e32 v92, 0xbfb8aa3b, v86
	v_add_f32_e32 v91, 1.0, v93
	v_mul_f32_e32 v93, 0xbfb8aa3b, v87
	v_exp_f32_e32 v92, v92
	v_exp_f32_e32 v93, v93
	v_rcp_f32_e32 v90, v90
	v_rcp_f32_e32 v91, v91
	v_add_f32_e32 v92, 1.0, v92
	v_add_f32_e32 v93, 1.0, v93
	v_rcp_f32_e32 v92, v92
	v_rcp_f32_e32 v93, v93
	v_pk_mul_f32 v[84:85], v[84:85], v[90:91]
	v_cvt_pk_bf16_f32 v107, v96, v97
	v_pk_mul_f32 v[80:81], v[84:85], v[80:81]
	v_mul_f32_e32 v84, 0xbfb8aa3b, v78
	v_cvt_pk_bf16_f32 v90, v80, v81
	v_pk_mul_f32 v[80:81], v[86:87], v[92:93]
	v_mul_f32_e32 v85, 0xbfb8aa3b, v79
	v_pk_mul_f32 v[80:81], v[80:81], v[82:83]
	v_mul_f32_e32 v82, 0xbfb8aa3b, v76
	v_mul_f32_e32 v83, 0xbfb8aa3b, v77
	v_exp_f32_e32 v82, v82
	v_exp_f32_e32 v83, v83
	v_exp_f32_e32 v84, v84
	v_exp_f32_e32 v85, v85
	v_add_f32_e32 v82, 1.0, v82
	v_add_f32_e32 v83, 1.0, v83
	v_rcp_f32_e32 v82, v82
	v_rcp_f32_e32 v83, v83
	v_add_f32_e32 v84, 1.0, v84
	v_add_f32_e32 v85, 1.0, v85
	v_rcp_f32_e32 v84, v84
	v_rcp_f32_e32 v85, v85
	v_pk_mul_f32 v[76:77], v[76:77], v[82:83]
	v_or_b32_e32 v96, 32, v154
	v_pk_mul_f32 v[72:73], v[76:77], v[72:73]
	v_pk_mul_f32 v[76:77], v[78:79], v[84:85]
	v_cvt_pk_bf16_f32 v72, v72, v73
	v_mul_f32_e32 v73, 0xbfb8aa3b, v68
; __device__ __forceinline__ unsigned pk2(float lo, float hi) { const f32x2c v = {lo, hi}; const bf16x2c b = __builtin_convertvector(v, bf16x2c); return __builtin_bit_cast(unsigned, b); }
; __device__ __forceinline__ float silu_f(float x) { return x * fast_sigmoid(x); }
;     __device__ __forceinline__ void operator()(const f32x4 (&acc)[2][2][4][2], const pg8::Unit& u, int wr, int wc, int fr, int fq) const {
;     ...
;                 const f32x4 a0 = acc[ai][0][m][0], a1 = acc[ai][0][m][1], b0 = acc[ai][1][m][0], b1 = acc[ai][1][m][1];
;                 u32x4 w;
;                 w.x = pk2(silu_f(a0[0]) * b0[0], silu_f(a0[1]) * b0[1]); w.y = pk2(silu_f(a0[2]) * b0[2], silu_f(a0[3]) * b0[3]);
;                 w.z = pk2(silu_f(a1[0]) * b1[0], silu_f(a1[1]) * b1[1]); w.w = pk2(silu_f(a1[2]) * b1[2], silu_f(a1[3]) * b1[3]);
	v_pk_mul_f32 v[74:75], v[76:77], v[74:75]
	v_exp_f32_e32 v76, v73
	v_mul_f32_e32 v73, 0xbfb8aa3b, v69
	v_exp_f32_e32 v77, v73
	v_cvt_pk_bf16_f32 v73, v74, v75
	v_add_f32_e32 v74, 1.0, v76
	v_mul_f32_e32 v76, 0xbfb8aa3b, v70
	v_add_f32_e32 v75, 1.0, v77
	v_mul_f32_e32 v77, 0xbfb8aa3b, v71
	v_exp_f32_e32 v76, v76
	v_exp_f32_e32 v77, v77
	v_rcp_f32_e32 v74, v74
	v_rcp_f32_e32 v75, v75
	v_add_f32_e32 v76, 1.0, v76
	v_add_f32_e32 v77, 1.0, v77
	v_rcp_f32_e32 v76, v76
	v_rcp_f32_e32 v77, v77
	v_pk_mul_f32 v[68:69], v[68:69], v[74:75]
	v_cvt_pk_bf16_f32 v91, v80, v81
	v_pk_mul_f32 v[64:65], v[68:69], v[64:65]
	v_mul_f32_e32 v68, 0xbfb8aa3b, v62
	v_cvt_pk_bf16_f32 v74, v64, v65
	v_pk_mul_f32 v[64:65], v[70:71], v[76:77]
	v_mul_f32_e32 v69, 0xbfb8aa3b, v63
	v_pk_mul_f32 v[64:65], v[64:65], v[66:67]
	v_mul_f32_e32 v66, 0xbfb8aa3b, v60
	v_mul_f32_e32 v67, 0xbfb8aa3b, v61
	v_exp_f32_e32 v66, v66
	v_exp_f32_e32 v67, v67
	v_exp_f32_e32 v68, v68
	v_exp_f32_e32 v69, v69
	v_add_f32_e32 v66, 1.0, v66
	v_add_f32_e32 v67, 1.0, v67
	v_rcp_f32_e32 v66, v66
	v_rcp_f32_e32 v67, v67
	v_add_f32_e32 v68, 1.0, v68
	v_add_f32_e32 v69, 1.0, v69
	v_rcp_f32_e32 v68, v68
	v_rcp_f32_e32 v69, v69
	v_pk_mul_f32 v[60:61], v[60:61], v[66:67]
	v_or_b32_e32 v80, 48, v154
	v_pk_mul_f32 v[56:57], v[60:61], v[56:57]
	v_pk_mul_f32 v[60:61], v[62:63], v[68:69]
	v_cvt_pk_bf16_f32 v56, v56, v57
	v_mul_f32_e32 v57, 0xbfb8aa3b, v52
	v_pk_mul_f32 v[58:59], v[60:61], v[58:59]
	v_exp_f32_e32 v60, v57
	v_mul_f32_e32 v57, 0xbfb8aa3b, v53
	v_exp_f32_e32 v61, v57
	v_cvt_pk_bf16_f32 v57, v58, v59
	v_add_f32_e32 v58, 1.0, v60
	v_mul_f32_e32 v60, 0xbfb8aa3b, v54
	v_add_f32_e32 v59, 1.0, v61
	v_mul_f32_e32 v61, 0xbfb8aa3b, v55
	v_exp_f32_e32 v60, v60
	v_exp_f32_e32 v61, v61
	v_rcp_f32_e32 v58, v58
	v_rcp_f32_e32 v59, v59
	v_add_f32_e32 v60, 1.0, v60
	v_add_f32_e32 v61, 1.0, v61
	v_rcp_f32_e32 v60, v60
	v_rcp_f32_e32 v61, v61
	v_pk_mul_f32 v[52:53], v[52:53], v[58:59]
	v_cvt_pk_bf16_f32 v75, v64, v65
	v_pk_mul_f32 v[48:49], v[52:53], v[48:49]
	v_mul_f32_e32 v52, 0xbfb8aa3b, v46
	v_cvt_pk_bf16_f32 v58, v48, v49
	v_pk_mul_f32 v[48:49], v[54:55], v[60:61]
	v_mul_f32_e32 v53, 0xbfb8aa3b, v47
	v_pk_mul_f32 v[48:49], v[48:49], v[50:51]
	v_mul_f32_e32 v50, 0xbfb8aa3b, v44
	v_mul_f32_e32 v51, 0xbfb8aa3b, v45
	v_exp_f32_e32 v50, v50
	v_exp_f32_e32 v51, v51
	v_exp_f32_e32 v52, v52
	v_exp_f32_e32 v53, v53
	v_add_f32_e32 v50, 1.0, v50
	v_add_f32_e32 v51, 1.0, v51
	v_rcp_f32_e32 v50, v50
	v_rcp_f32_e32 v51, v51
	v_add_f32_e32 v52, 1.0, v52
	v_add_f32_e32 v53, 1.0, v53
	v_rcp_f32_e32 v52, v52
	v_rcp_f32_e32 v53, v53
	v_pk_mul_f32 v[44:45], v[44:45], v[50:51]
	v_add_u32_e32 v64, 0x80, v154
	v_pk_mul_f32 v[40:41], v[44:45], v[40:41]
	v_pk_mul_f32 v[44:45], v[46:47], v[52:53]
	v_cvt_pk_bf16_f32 v40, v40, v41
	v_mul_f32_e32 v41, 0xbfb8aa3b, v36
	v_pk_mul_f32 v[42:43], v[44:45], v[42:43]
	v_exp_f32_e32 v44, v41
	v_mul_f32_e32 v41, 0xbfb8aa3b, v37
	v_exp_f32_e32 v45, v41
	v_cvt_pk_bf16_f32 v41, v42, v43
	v_add_f32_e32 v42, 1.0, v44
	v_mul_f32_e32 v44, 0xbfb8aa3b, v38
	v_add_f32_e32 v43, 1.0, v45
	v_mul_f32_e32 v45, 0xbfb8aa3b, v39
	v_exp_f32_e32 v44, v44
	v_exp_f32_e32 v45, v45
	v_rcp_f32_e32 v42, v42
	v_rcp_f32_e32 v43, v43
	v_add_f32_e32 v44, 1.0, v44
	v_add_f32_e32 v45, 1.0, v45
	v_rcp_f32_e32 v44, v44
	v_rcp_f32_e32 v45, v45
	v_pk_mul_f32 v[36:37], v[36:37], v[42:43]
	v_cvt_pk_bf16_f32 v59, v48, v49
	v_pk_mul_f32 v[32:33], v[36:37], v[32:33]
	v_mul_f32_e32 v36, 0xbfb8aa3b, v30
	v_cvt_pk_bf16_f32 v42, v32, v33
	v_pk_mul_f32 v[32:33], v[38:39], v[44:45]
	v_mul_f32_e32 v37, 0xbfb8aa3b, v31
	v_pk_mul_f32 v[32:33], v[32:33], v[34:35]
	v_mul_f32_e32 v34, 0xbfb8aa3b, v28
	v_mul_f32_e32 v35, 0xbfb8aa3b, v29
	v_exp_f32_e32 v34, v34
	v_exp_f32_e32 v35, v35
	v_exp_f32_e32 v36, v36
	v_exp_f32_e32 v37, v37
	v_add_f32_e32 v34, 1.0, v34
	v_add_f32_e32 v35, 1.0, v35
	v_rcp_f32_e32 v34, v34
	v_rcp_f32_e32 v35, v35
	v_add_f32_e32 v36, 1.0, v36
; __device__ __forceinline__ unsigned pk2(float lo, float hi) { const f32x2c v = {lo, hi}; const bf16x2c b = __builtin_convertvector(v, bf16x2c); return __builtin_bit_cast(unsigned, b); }
; __device__ __forceinline__ float silu_f(float x) { return x * fast_sigmoid(x); }
;     __device__ __forceinline__ void operator()(const f32x4 (&acc)[2][2][4][2], const pg8::Unit& u, int wr, int wc, int fr, int fq) const {
;     ...
;                 bf16_t* rowp = O + (size_t)(row0 + ai * 128 + m * 16) * ldc + col0;
;                 const f32x4 a0 = acc[ai][0][m][0], a1 = acc[ai][0][m][1], b0 = acc[ai][1][m][0], b1 = acc[ai][1][m][1];
;                 u32x4 w;
;                 w.x = pk2(silu_f(a0[0]) * b0[0], silu_f(a0[1]) * b0[1]); w.y = pk2(silu_f(a0[2]) * b0[2], silu_f(a0[3]) * b0[3]);
;                 w.z = pk2(silu_f(a1[0]) * b1[0], silu_f(a1[1]) * b1[1]); w.w = pk2(silu_f(a1[2]) * b1[2], silu_f(a1[3]) * b1[3]);
;                 *(u32x4*)rowp = w;
;             }
	v_add_f32_e32 v37, 1.0, v37
	v_rcp_f32_e32 v36, v36
	v_rcp_f32_e32 v37, v37
	v_pk_mul_f32 v[28:29], v[28:29], v[34:35]
	v_add_u32_e32 v48, 0x90, v154
	v_pk_mul_f32 v[24:25], v[28:29], v[24:25]
	v_pk_mul_f32 v[28:29], v[30:31], v[36:37]
	v_cvt_pk_bf16_f32 v24, v24, v25
	v_mul_f32_e32 v25, 0xbfb8aa3b, v20
	v_pk_mul_f32 v[26:27], v[28:29], v[26:27]
	v_exp_f32_e32 v28, v25
	v_mul_f32_e32 v25, 0xbfb8aa3b, v21
	v_exp_f32_e32 v29, v25
	v_cvt_pk_bf16_f32 v25, v26, v27
	v_add_f32_e32 v26, 1.0, v28
	v_mul_f32_e32 v28, 0xbfb8aa3b, v22
	v_add_f32_e32 v27, 1.0, v29
	v_mul_f32_e32 v29, 0xbfb8aa3b, v23
	v_exp_f32_e32 v28, v28
	v_exp_f32_e32 v29, v29
	v_rcp_f32_e32 v26, v26
	v_rcp_f32_e32 v27, v27
	v_add_f32_e32 v28, 1.0, v28
	v_add_f32_e32 v29, 1.0, v29
	v_rcp_f32_e32 v28, v28
	v_rcp_f32_e32 v29, v29
	v_pk_mul_f32 v[20:21], v[20:21], v[26:27]
	v_cvt_pk_bf16_f32 v43, v32, v33
	v_pk_mul_f32 v[16:17], v[20:21], v[16:17]
	v_mul_f32_e32 v20, 0xbfb8aa3b, v14
	v_cvt_pk_bf16_f32 v26, v16, v17
	v_pk_mul_f32 v[16:17], v[22:23], v[28:29]
	v_mul_f32_e32 v21, 0xbfb8aa3b, v15
	v_pk_mul_f32 v[16:17], v[16:17], v[18:19]
	v_mul_f32_e32 v18, 0xbfb8aa3b, v12
	v_mul_f32_e32 v19, 0xbfb8aa3b, v13
	v_exp_f32_e32 v18, v18
	v_exp_f32_e32 v19, v19
	v_exp_f32_e32 v20, v20
	v_exp_f32_e32 v21, v21
	v_add_f32_e32 v18, 1.0, v18
	v_add_f32_e32 v19, 1.0, v19
	v_rcp_f32_e32 v18, v18
	v_rcp_f32_e32 v19, v19
	v_add_f32_e32 v20, 1.0, v20
	v_add_f32_e32 v21, 1.0, v21
	v_rcp_f32_e32 v20, v20
	v_rcp_f32_e32 v21, v21
	v_pk_mul_f32 v[12:13], v[12:13], v[18:19]
	v_add_u32_e32 v32, 0xa0, v154
	v_pk_mul_f32 v[8:9], v[12:13], v[8:9]
	v_pk_mul_f32 v[12:13], v[14:15], v[20:21]
	v_cvt_pk_bf16_f32 v8, v8, v9
	v_mul_f32_e32 v9, 0xbfb8aa3b, v4
	v_pk_mul_f32 v[10:11], v[12:13], v[10:11]
	v_exp_f32_e32 v12, v9
	v_mul_f32_e32 v9, 0xbfb8aa3b, v5
	v_exp_f32_e32 v13, v9
	v_cvt_pk_bf16_f32 v9, v10, v11
	v_add_f32_e32 v10, 1.0, v12
	v_mul_f32_e32 v12, 0xbfb8aa3b, v6
	v_add_f32_e32 v11, 1.0, v13
	v_mul_f32_e32 v13, 0xbfb8aa3b, v7
	v_exp_f32_e32 v12, v12
	v_exp_f32_e32 v13, v13
	v_rcp_f32_e32 v10, v10
	v_rcp_f32_e32 v11, v11
	v_add_f32_e32 v12, 1.0, v12
	v_add_f32_e32 v13, 1.0, v13
	v_rcp_f32_e32 v12, v12
	v_rcp_f32_e32 v13, v13
	v_pk_mul_f32 v[4:5], v[4:5], v[10:11]
	v_cvt_pk_bf16_f32 v27, v16, v17
	v_pk_mul_f32 v[0:1], v[4:5], v[0:1]
	v_add_u32_e32 v16, 0xb0, v154
	v_cvt_pk_bf16_f32 v10, v0, v1
	v_pk_mul_f32 v[0:1], v[6:7], v[12:13]
	v_mad_i64_i32 v[156:157], s[30:31], v154, s70, v[146:147]
	v_lshlrev_b64 v[144:145], 1, v[144:145]
	v_mad_i64_i32 v[112:113], s[30:31], v112, s70, v[146:147]
	v_mad_i64_i32 v[96:97], s[30:31], v96, s70, v[146:147]
	v_mad_i64_i32 v[80:81], s[30:31], v80, s70, v[146:147]
	v_mad_i64_i32 v[64:65], s[30:31], v64, s70, v[146:147]
	v_mad_i64_i32 v[48:49], s[30:31], v48, s70, v[146:147]
	v_mad_i64_i32 v[32:33], s[30:31], v32, s70, v[146:147]
	v_mad_i64_i32 v[16:17], s[30:31], v16, s70, v[146:147]
	v_pk_mul_f32 v[0:1], v[0:1], v[2:3]
	v_lshl_add_u64 v[156:157], v[156:157], 0, v[144:145]
	v_lshl_add_u64 v[112:113], v[112:113], 0, v[144:145]
	v_lshl_add_u64 v[96:97], v[96:97], 0, v[144:145]
	v_lshl_add_u64 v[80:81], v[80:81], 0, v[144:145]
	v_lshl_add_u64 v[64:65], v[64:65], 0, v[144:145]
	v_lshl_add_u64 v[48:49], v[48:49], 0, v[144:145]
	v_lshl_add_u64 v[32:33], v[32:33], 0, v[144:145]
	v_lshl_add_u64 v[16:17], v[16:17], 0, v[144:145]
	v_cvt_pk_bf16_f32 v11, v0, v1
	s_andn2_b64 vcc, exec, s[4:5]
	s_mov_b64 s[4:5], -1
	global_store_dwordx4 v[156:157], v[120:123], off nt
	global_store_dwordx4 v[112:113], v[104:107], off nt
	global_store_dwordx4 v[96:97], v[88:91], off nt
	global_store_dwordx4 v[80:81], v[72:75], off nt
	global_store_dwordx4 v[64:65], v[56:59], off nt
	global_store_dwordx4 v[48:49], v[40:43], off nt
	global_store_dwordx4 v[32:33], v[24:27], off nt
	global_store_dwordx4 v[16:17], v[8:11], off nt
	s_cbranch_vccnz .LBB0_146
	s_andn2_b64 vcc, exec, s[6:7]
	s_cbranch_vccnz .LBB0_145
	s_barrier
	s_branch .LBB0_145

; __device__ __forceinline__ unsigned pk2(float lo, float hi) { const f32x2c v = {lo, hi}; const bf16x2c b = __builtin_convertvector(v, bf16x2c); return __builtin_bit_cast(unsigned, b); }
; __device__ __forceinline__ float silu_f(float x) { return x * fast_sigmoid(x); }
;     __device__ __forceinline__ void operator()(const f32x4 (&acc)[2][2][4][2], const pg8::Unit& u, int wr, int wc, int fr, int fq) const {
;         const int row0 = u.pm * 256 + wr * 64 + fr, col0 = u.pn * 128 + wc * 32 + 8 * fq;
; #pragma unroll
;         for (int ai = 0; ai < 2; ++ai)
; #pragma unroll
;             for (int m = 0; m < 4; ++m) {
;                 bf16_t* rowp = O + (size_t)(row0 + ai * 128 + m * 16) * ldc + col0;
;                 const f32x4 a0 = acc[ai][0][m][0], a1 = acc[ai][0][m][1], b0 = acc[ai][1][m][0], b1 = acc[ai][1][m][1];
;                 u32x4 w;
;                 w.x = pk2(silu_f(a0[0]) * b0[0], silu_f(a0[1]) * b0[1]); w.y = pk2(silu_f(a0[2]) * b0[2], silu_f(a0[3]) * b0[3]);
;                 w.z = pk2(silu_f(a1[0]) * b1[0], silu_f(a1[1]) * b1[1]); w.w = pk2(silu_f(a1[2]) * b1[2], silu_f(a1[3]) * b1[3]);
.LBB0_1314:
	v_mul_f32_e32 v155, 0xbfb8aa3b, v124
	v_exp_f32_e32 v155, v155
	v_mul_f32_e32 v158, 0xbfb8aa3b, v125
	v_exp_f32_e32 v159, v158
	v_lshl_add_u32 v154, s20, 8, v148
	v_add_f32_e32 v155, 1.0, v155
	v_rcp_f32_e32 v158, v155
	v_add_f32_e32 v155, 1.0, v159
	v_mul_f32_e32 v159, 0xbfb8aa3b, v126
	v_exp_f32_e32 v160, v159
	v_mul_f32_e32 v159, 0xbfb8aa3b, v127
	v_exp_f32_e32 v161, v159
	v_rcp_f32_e32 v159, v155
	v_add_f32_e32 v155, 1.0, v160
	v_rcp_f32_e32 v160, v155
	v_add_f32_e32 v155, 1.0, v161
	v_rcp_f32_e32 v161, v155
	v_pk_mul_f32 v[124:125], v[124:125], v[158:159]
	v_lshl_add_u32 v144, s45, 7, v150
	v_pk_mul_f32 v[120:121], v[124:125], v[120:121]
	v_pk_mul_f32 v[124:125], v[126:127], v[160:161]
	v_cvt_pk_bf16_f32 v120, v120, v121
	v_mul_f32_e32 v121, 0xbfb8aa3b, v116
	v_pk_mul_f32 v[122:123], v[124:125], v[122:123]
	v_exp_f32_e32 v124, v121
	v_mul_f32_e32 v121, 0xbfb8aa3b, v117
	v_exp_f32_e32 v125, v121
	v_cvt_pk_bf16_f32 v121, v122, v123
	v_add_f32_e32 v122, 1.0, v124
	v_mul_f32_e32 v124, 0xbfb8aa3b, v118
	v_add_f32_e32 v123, 1.0, v125
	v_mul_f32_e32 v125, 0xbfb8aa3b, v119
	v_exp_f32_e32 v124, v124
	v_exp_f32_e32 v125, v125
	v_rcp_f32_e32 v122, v122
	v_rcp_f32_e32 v123, v123
	v_add_f32_e32 v124, 1.0, v124
	v_add_f32_e32 v125, 1.0, v125
	v_rcp_f32_e32 v124, v124
	v_rcp_f32_e32 v125, v125
	v_pk_mul_f32 v[116:117], v[116:117], v[122:123]
	v_ashrrev_i32_e32 v145, 31, v144
	v_pk_mul_f32 v[112:113], v[116:117], v[112:113]
	v_mul_f32_e32 v116, 0xbfb8aa3b, v110
	v_cvt_pk_bf16_f32 v122, v112, v113
	v_pk_mul_f32 v[112:113], v[118:119], v[124:125]
	v_mul_f32_e32 v117, 0xbfb8aa3b, v111
	v_pk_mul_f32 v[112:113], v[112:113], v[114:115]
	v_mul_f32_e32 v114, 0xbfb8aa3b, v108
	v_mul_f32_e32 v115, 0xbfb8aa3b, v109
	v_exp_f32_e32 v114, v114
	v_exp_f32_e32 v115, v115
	v_exp_f32_e32 v116, v116
	v_exp_f32_e32 v117, v117
	v_add_f32_e32 v114, 1.0, v114
	v_add_f32_e32 v115, 1.0, v115
	v_rcp_f32_e32 v114, v114
	v_rcp_f32_e32 v115, v115
	v_add_f32_e32 v116, 1.0, v116
	v_add_f32_e32 v117, 1.0, v117
	v_rcp_f32_e32 v116, v116
	v_rcp_f32_e32 v117, v117
	v_pk_mul_f32 v[108:109], v[108:109], v[114:115]
	s_cselect_b32 s98, 1, 0
	s_lshr_b32 s99, s20, 1
	s_and_b32 s100, s99, 7
	s_lshl_b32 s100, s100, 1
	s_bfe_u32 s101, s99, 0x10003
	s_or_b32 s100, s100, s101
	s_and_b32 s101, s99, 0x30
	s_or_b32 s100, s100, s101
	s_mul_i32 s100, s100, 0x300000
	s_mul_i32 s99, s99, 0x2c0000
	s_add_u32 s100, s100, 0xd000000
	s_sub_u32 s100, s100, s99
	s_add_u32 s100, s96, s100
	s_addc_u32 s101, s97, 0
	s_cmp_lg_u32 s98, 0
	v_mov_b64_e32 v[146:147], s[100:101]
	v_pk_mul_f32 v[104:105], v[108:109], v[104:105]
	v_pk_mul_f32 v[108:109], v[110:111], v[116:117]
	v_cvt_pk_bf16_f32 v104, v104, v105
	v_mul_f32_e32 v105, 0xbfb8aa3b, v100
	v_pk_mul_f32 v[106:107], v[108:109], v[106:107]
	v_exp_f32_e32 v108, v105
	v_mul_f32_e32 v105, 0xbfb8aa3b, v101
	v_exp_f32_e32 v109, v105
	v_cvt_pk_bf16_f32 v105, v106, v107
	v_add_f32_e32 v106, 1.0, v108
	v_mul_f32_e32 v108, 0xbfb8aa3b, v102
	v_add_f32_e32 v107, 1.0, v109
	v_mul_f32_e32 v109, 0xbfb8aa3b, v103
	v_exp_f32_e32 v108, v108
	v_exp_f32_e32 v109, v109
	v_rcp_f32_e32 v106, v106
	v_rcp_f32_e32 v107, v107
	v_add_f32_e32 v108, 1.0, v108
	v_add_f32_e32 v109, 1.0, v109
	v_rcp_f32_e32 v108, v108
	v_rcp_f32_e32 v109, v109
	v_pk_mul_f32 v[100:101], v[100:101], v[106:107]
	v_cvt_pk_bf16_f32 v123, v112, v113
	v_pk_mul_f32 v[96:97], v[100:101], v[96:97]
	v_mul_f32_e32 v100, 0xbfb8aa3b, v94
	v_cvt_pk_bf16_f32 v106, v96, v97
	v_pk_mul_f32 v[96:97], v[102:103], v[108:109]
	v_mul_f32_e32 v101, 0xbfb8aa3b, v95
	v_pk_mul_f32 v[96:97], v[96:97], v[98:99]
	v_mul_f32_e32 v98, 0xbfb8aa3b, v92
	v_mul_f32_e32 v99, 0xbfb8aa3b, v93
	v_exp_f32_e32 v98, v98
	v_exp_f32_e32 v99, v99
	v_exp_f32_e32 v100, v100
	v_exp_f32_e32 v101, v101
	v_add_f32_e32 v98, 1.0, v98
	v_add_f32_e32 v99, 1.0, v99
	v_rcp_f32_e32 v98, v98
	v_rcp_f32_e32 v99, v99
	v_add_f32_e32 v100, 1.0, v100
	v_add_f32_e32 v101, 1.0, v101
	v_rcp_f32_e32 v100, v100
	v_rcp_f32_e32 v101, v101
	v_pk_mul_f32 v[92:93], v[92:93], v[98:99]
	v_or_b32_e32 v112, 16, v154
	v_pk_mul_f32 v[88:89], v[92:93], v[88:89]
	v_pk_mul_f32 v[92:93], v[94:95], v[100:101]
	v_cvt_pk_bf16_f32 v88, v88, v89
	v_mul_f32_e32 v89, 0xbfb8aa3b, v84
	v_pk_mul_f32 v[90:91], v[92:93], v[90:91]
	v_exp_f32_e32 v92, v89
	v_mul_f32_e32 v89, 0xbfb8aa3b, v85
	v_exp_f32_e32 v93, v89
	v_cvt_pk_bf16_f32 v89, v90, v91
	v_add_f32_e32 v90, 1.0, v92
	v_mul_f32_e32 v92, 0xbfb8aa3b, v86
	v_add_f32_e32 v91, 1.0, v93
	v_mul_f32_e32 v93, 0xbfb8aa3b, v87
	v_exp_f32_e32 v92, v92
	v_exp_f32_e32 v93, v93
	v_rcp_f32_e32 v90, v90
	v_rcp_f32_e32 v91, v91
	v_add_f32_e32 v92, 1.0, v92
	v_add_f32_e32 v93, 1.0, v93
	v_rcp_f32_e32 v92, v92
	v_rcp_f32_e32 v93, v93
	v_pk_mul_f32 v[84:85], v[84:85], v[90:91]
	v_cvt_pk_bf16_f32 v107, v96, v97
	v_pk_mul_f32 v[80:81], v[84:85], v[80:81]
	v_mul_f32_e32 v84, 0xbfb8aa3b, v78
	v_cvt_pk_bf16_f32 v90, v80, v81
	v_pk_mul_f32 v[80:81], v[86:87], v[92:93]
	v_mul_f32_e32 v85, 0xbfb8aa3b, v79
	v_pk_mul_f32 v[80:81], v[80:81], v[82:83]
	v_mul_f32_e32 v82, 0xbfb8aa3b, v76
	v_mul_f32_e32 v83, 0xbfb8aa3b, v77
	v_exp_f32_e32 v82, v82
	v_exp_f32_e32 v83, v83
	v_exp_f32_e32 v84, v84
	v_exp_f32_e32 v85, v85
	v_add_f32_e32 v82, 1.0, v82
	v_add_f32_e32 v83, 1.0, v83
	v_rcp_f32_e32 v82, v82
	v_rcp_f32_e32 v83, v83
	v_add_f32_e32 v84, 1.0, v84
	v_add_f32_e32 v85, 1.0, v85
	v_rcp_f32_e32 v84, v84
	v_rcp_f32_e32 v85, v85
	v_pk_mul_f32 v[76:77], v[76:77], v[82:83]
	v_or_b32_e32 v96, 32, v154
	v_pk_mul_f32 v[72:73], v[76:77], v[72:73]
	v_pk_mul_f32 v[76:77], v[78:79], v[84:85]
	v_cvt_pk_bf16_f32 v72, v72, v73
	v_mul_f32_e32 v73, 0xbfb8aa3b, v68
; __device__ __forceinline__ unsigned pk2(float lo, float hi) { const f32x2c v = {lo, hi}; const bf16x2c b = __builtin_convertvector(v, bf16x2c); return __builtin_bit_cast(unsigned, b); }
; __device__ __forceinline__ float silu_f(float x) { return x * fast_sigmoid(x); }
;     __device__ __forceinline__ void operator()(const f32x4 (&acc)[2][2][4][2], const pg8::Unit& u, int wr, int wc, int fr, int fq) const {
;     ...
;                 const f32x4 a0 = acc[ai][0][m][0], a1 = acc[ai][0][m][1], b0 = acc[ai][1][m][0], b1 = acc[ai][1][m][1];
;                 u32x4 w;
;                 w.x = pk2(silu_f(a0[0]) * b0[0], silu_f(a0[1]) * b0[1]); w.y = pk2(silu_f(a0[2]) * b0[2], silu_f(a0[3]) * b0[3]);
;                 w.z = pk2(silu_f(a1[0]) * b1[0], silu_f(a1[1]) * b1[1]); w.w = pk2(silu_f(a1[2]) * b1[2], silu_f(a1[3]) * b1[3]);
	v_pk_mul_f32 v[74:75], v[76:77], v[74:75]
	v_exp_f32_e32 v76, v73
	v_mul_f32_e32 v73, 0xbfb8aa3b, v69
	v_exp_f32_e32 v77, v73
	v_cvt_pk_bf16_f32 v73, v74, v75
	v_add_f32_e32 v74, 1.0, v76
	v_mul_f32_e32 v76, 0xbfb8aa3b, v70
	v_add_f32_e32 v75, 1.0, v77
	v_mul_f32_e32 v77, 0xbfb8aa3b, v71
	v_exp_f32_e32 v76, v76
	v_exp_f32_e32 v77, v77
	v_rcp_f32_e32 v74, v74
	v_rcp_f32_e32 v75, v75
	v_add_f32_e32 v76, 1.0, v76
	v_add_f32_e32 v77, 1.0, v77
	v_rcp_f32_e32 v76, v76
	v_rcp_f32_e32 v77, v77
	v_pk_mul_f32 v[68:69], v[68:69], v[74:75]
	v_cvt_pk_bf16_f32 v91, v80, v81
	v_pk_mul_f32 v[64:65], v[68:69], v[64:65]
	v_mul_f32_e32 v68, 0xbfb8aa3b, v62
	v_cvt_pk_bf16_f32 v74, v64, v65
	v_pk_mul_f32 v[64:65], v[70:71], v[76:77]
	v_mul_f32_e32 v69, 0xbfb8aa3b, v63
	v_pk_mul_f32 v[64:65], v[64:65], v[66:67]
	v_mul_f32_e32 v66, 0xbfb8aa3b, v60
	v_mul_f32_e32 v67, 0xbfb8aa3b, v61
	v_exp_f32_e32 v66, v66
	v_exp_f32_e32 v67, v67
	v_exp_f32_e32 v68, v68
	v_exp_f32_e32 v69, v69
	v_add_f32_e32 v66, 1.0, v66
	v_add_f32_e32 v67, 1.0, v67
	v_rcp_f32_e32 v66, v66
	v_rcp_f32_e32 v67, v67
	v_add_f32_e32 v68, 1.0, v68
	v_add_f32_e32 v69, 1.0, v69
	v_rcp_f32_e32 v68, v68
	v_rcp_f32_e32 v69, v69
	v_pk_mul_f32 v[60:61], v[60:61], v[66:67]
	v_or_b32_e32 v80, 48, v154
	v_pk_mul_f32 v[56:57], v[60:61], v[56:57]
	v_pk_mul_f32 v[60:61], v[62:63], v[68:69]
	v_cvt_pk_bf16_f32 v56, v56, v57
	v_mul_f32_e32 v57, 0xbfb8aa3b, v52
	v_pk_mul_f32 v[58:59], v[60:61], v[58:59]
	v_exp_f32_e32 v60, v57
	v_mul_f32_e32 v57, 0xbfb8aa3b, v53
	v_exp_f32_e32 v61, v57
	v_cvt_pk_bf16_f32 v57, v58, v59
	v_add_f32_e32 v58, 1.0, v60
	v_mul_f32_e32 v60, 0xbfb8aa3b, v54
	v_add_f32_e32 v59, 1.0, v61
	v_mul_f32_e32 v61, 0xbfb8aa3b, v55
	v_exp_f32_e32 v60, v60
	v_exp_f32_e32 v61, v61
	v_rcp_f32_e32 v58, v58
	v_rcp_f32_e32 v59, v59
	v_add_f32_e32 v60, 1.0, v60
	v_add_f32_e32 v61, 1.0, v61
	v_rcp_f32_e32 v60, v60
	v_rcp_f32_e32 v61, v61
	v_pk_mul_f32 v[52:53], v[52:53], v[58:59]
	v_cvt_pk_bf16_f32 v75, v64, v65
	v_pk_mul_f32 v[48:49], v[52:53], v[48:49]
	v_mul_f32_e32 v52, 0xbfb8aa3b, v46
	v_cvt_pk_bf16_f32 v58, v48, v49
	v_pk_mul_f32 v[48:49], v[54:55], v[60:61]
	v_mul_f32_e32 v53, 0xbfb8aa3b, v47
	v_pk_mul_f32 v[48:49], v[48:49], v[50:51]
	v_mul_f32_e32 v50, 0xbfb8aa3b, v44
	v_mul_f32_e32 v51, 0xbfb8aa3b, v45
	v_exp_f32_e32 v50, v50
	v_exp_f32_e32 v51, v51
	v_exp_f32_e32 v52, v52
	v_exp_f32_e32 v53, v53
	v_add_f32_e32 v50, 1.0, v50
	v_add_f32_e32 v51, 1.0, v51
	v_rcp_f32_e32 v50, v50
	v_rcp_f32_e32 v51, v51
	v_add_f32_e32 v52, 1.0, v52
	v_add_f32_e32 v53, 1.0, v53
	v_rcp_f32_e32 v52, v52
	v_rcp_f32_e32 v53, v53
	v_pk_mul_f32 v[44:45], v[44:45], v[50:51]
	v_add_u32_e32 v64, 0x80, v154
	v_pk_mul_f32 v[40:41], v[44:45], v[40:41]
	v_pk_mul_f32 v[44:45], v[46:47], v[52:53]
	v_cvt_pk_bf16_f32 v40, v40, v41
	v_mul_f32_e32 v41, 0xbfb8aa3b, v36
	v_pk_mul_f32 v[42:43], v[44:45], v[42:43]
	v_exp_f32_e32 v44, v41
	v_mul_f32_e32 v41, 0xbfb8aa3b, v37
	v_exp_f32_e32 v45, v41
	v_cvt_pk_bf16_f32 v41, v42, v43
	v_add_f32_e32 v42, 1.0, v44
	v_mul_f32_e32 v44, 0xbfb8aa3b, v38
	v_add_f32_e32 v43, 1.0, v45
	v_mul_f32_e32 v45, 0xbfb8aa3b, v39
	v_exp_f32_e32 v44, v44
	v_exp_f32_e32 v45, v45
	v_rcp_f32_e32 v42, v42
	v_rcp_f32_e32 v43, v43
	v_add_f32_e32 v44, 1.0, v44
	v_add_f32_e32 v45, 1.0, v45
	v_rcp_f32_e32 v44, v44
	v_rcp_f32_e32 v45, v45
	v_pk_mul_f32 v[36:37], v[36:37], v[42:43]
	v_cvt_pk_bf16_f32 v59, v48, v49
	v_pk_mul_f32 v[32:33], v[36:37], v[32:33]
	v_mul_f32_e32 v36, 0xbfb8aa3b, v30
	v_cvt_pk_bf16_f32 v42, v32, v33
	v_pk_mul_f32 v[32:33], v[38:39], v[44:45]
	v_mul_f32_e32 v37, 0xbfb8aa3b, v31
	v_pk_mul_f32 v[32:33], v[32:33], v[34:35]
	v_mul_f32_e32 v34, 0xbfb8aa3b, v28
	v_mul_f32_e32 v35, 0xbfb8aa3b, v29
	v_exp_f32_e32 v34, v34
	v_exp_f32_e32 v35, v35
	v_exp_f32_e32 v36, v36
	v_exp_f32_e32 v37, v37
	v_add_f32_e32 v34, 1.0, v34
	v_add_f32_e32 v35, 1.0, v35
	v_rcp_f32_e32 v34, v34
	v_rcp_f32_e32 v35, v35
	v_add_f32_e32 v36, 1.0, v36
; __device__ __forceinline__ unsigned pk2(float lo, float hi) { const f32x2c v = {lo, hi}; const bf16x2c b = __builtin_convertvector(v, bf16x2c); return __builtin_bit_cast(unsigned, b); }
; __device__ __forceinline__ float silu_f(float x) { return x * fast_sigmoid(x); }
;     __device__ __forceinline__ void operator()(const f32x4 (&acc)[2][2][4][2], const pg8::Unit& u, int wr, int wc, int fr, int fq) const {
;     ...
;                 bf16_t* rowp = O + (size_t)(row0 + ai * 128 + m * 16) * ldc + col0;
;                 const f32x4 a0 = acc[ai][0][m][0], a1 = acc[ai][0][m][1], b0 = acc[ai][1][m][0], b1 = acc[ai][1][m][1];
;                 u32x4 w;
;                 w.x = pk2(silu_f(a0[0]) * b0[0], silu_f(a0[1]) * b0[1]); w.y = pk2(silu_f(a0[2]) * b0[2], silu_f(a0[3]) * b0[3]);
;                 w.z = pk2(silu_f(a1[0]) * b1[0], silu_f(a1[1]) * b1[1]); w.w = pk2(silu_f(a1[2]) * b1[2], silu_f(a1[3]) * b1[3]);
;                 *(u32x4*)rowp = w;
;             }
	v_add_f32_e32 v37, 1.0, v37
	v_rcp_f32_e32 v36, v36
	v_rcp_f32_e32 v37, v37
	v_pk_mul_f32 v[28:29], v[28:29], v[34:35]
	v_add_u32_e32 v48, 0x90, v154
	v_pk_mul_f32 v[24:25], v[28:29], v[24:25]
	v_pk_mul_f32 v[28:29], v[30:31], v[36:37]
	v_cvt_pk_bf16_f32 v24, v24, v25
	v_mul_f32_e32 v25, 0xbfb8aa3b, v20
	v_pk_mul_f32 v[26:27], v[28:29], v[26:27]
	v_exp_f32_e32 v28, v25
	v_mul_f32_e32 v25, 0xbfb8aa3b, v21
	v_exp_f32_e32 v29, v25
	v_cvt_pk_bf16_f32 v25, v26, v27
	v_add_f32_e32 v26, 1.0, v28
	v_mul_f32_e32 v28, 0xbfb8aa3b, v22
	v_add_f32_e32 v27, 1.0, v29
	v_mul_f32_e32 v29, 0xbfb8aa3b, v23
	v_exp_f32_e32 v28, v28
	v_exp_f32_e32 v29, v29
	v_rcp_f32_e32 v26, v26
	v_rcp_f32_e32 v27, v27
	v_add_f32_e32 v28, 1.0, v28
	v_add_f32_e32 v29, 1.0, v29
	v_rcp_f32_e32 v28, v28
	v_rcp_f32_e32 v29, v29
	v_pk_mul_f32 v[20:21], v[20:21], v[26:27]
	v_cvt_pk_bf16_f32 v43, v32, v33
	v_pk_mul_f32 v[16:17], v[20:21], v[16:17]
	v_mul_f32_e32 v20, 0xbfb8aa3b, v14
	v_cvt_pk_bf16_f32 v26, v16, v17
	v_pk_mul_f32 v[16:17], v[22:23], v[28:29]
	v_mul_f32_e32 v21, 0xbfb8aa3b, v15
	v_pk_mul_f32 v[16:17], v[16:17], v[18:19]
	v_mul_f32_e32 v18, 0xbfb8aa3b, v12
	v_mul_f32_e32 v19, 0xbfb8aa3b, v13
	v_exp_f32_e32 v18, v18
	v_exp_f32_e32 v19, v19
	v_exp_f32_e32 v20, v20
	v_exp_f32_e32 v21, v21
	v_add_f32_e32 v18, 1.0, v18
	v_add_f32_e32 v19, 1.0, v19
	v_rcp_f32_e32 v18, v18
	v_rcp_f32_e32 v19, v19
	v_add_f32_e32 v20, 1.0, v20
	v_add_f32_e32 v21, 1.0, v21
	v_rcp_f32_e32 v20, v20
	v_rcp_f32_e32 v21, v21
	v_pk_mul_f32 v[12:13], v[12:13], v[18:19]
	v_add_u32_e32 v32, 0xa0, v154
	v_pk_mul_f32 v[8:9], v[12:13], v[8:9]
	v_pk_mul_f32 v[12:13], v[14:15], v[20:21]
	v_cvt_pk_bf16_f32 v8, v8, v9
	v_mul_f32_e32 v9, 0xbfb8aa3b, v4
	v_pk_mul_f32 v[10:11], v[12:13], v[10:11]
	v_exp_f32_e32 v12, v9
	v_mul_f32_e32 v9, 0xbfb8aa3b, v5
	v_exp_f32_e32 v13, v9
	v_cvt_pk_bf16_f32 v9, v10, v11
	v_add_f32_e32 v10, 1.0, v12
	v_mul_f32_e32 v12, 0xbfb8aa3b, v6
	v_add_f32_e32 v11, 1.0, v13
	v_mul_f32_e32 v13, 0xbfb8aa3b, v7
	v_exp_f32_e32 v12, v12
	v_exp_f32_e32 v13, v13
	v_rcp_f32_e32 v10, v10
	v_rcp_f32_e32 v11, v11
	v_add_f32_e32 v12, 1.0, v12
	v_add_f32_e32 v13, 1.0, v13
	v_rcp_f32_e32 v12, v12
	v_rcp_f32_e32 v13, v13
	v_pk_mul_f32 v[4:5], v[4:5], v[10:11]
	v_cvt_pk_bf16_f32 v27, v16, v17
	v_pk_mul_f32 v[0:1], v[4:5], v[0:1]
	v_add_u32_e32 v16, 0xb0, v154
	v_cvt_pk_bf16_f32 v10, v0, v1
	v_pk_mul_f32 v[0:1], v[6:7], v[12:13]
	v_mad_i64_i32 v[156:157], s[22:23], v154, s44, v[146:147]
	v_lshlrev_b64 v[144:145], 1, v[144:145]
	v_mad_i64_i32 v[112:113], s[22:23], v112, s44, v[146:147]
	v_mad_i64_i32 v[96:97], s[22:23], v96, s44, v[146:147]
	v_mad_i64_i32 v[80:81], s[22:23], v80, s44, v[146:147]
	v_mad_i64_i32 v[64:65], s[22:23], v64, s44, v[146:147]
	v_mad_i64_i32 v[48:49], s[22:23], v48, s44, v[146:147]
	v_mad_i64_i32 v[32:33], s[22:23], v32, s44, v[146:147]
	v_mad_i64_i32 v[16:17], s[22:23], v16, s44, v[146:147]
	v_pk_mul_f32 v[0:1], v[0:1], v[2:3]
	v_lshl_add_u64 v[156:157], v[156:157], 0, v[144:145]
	v_lshl_add_u64 v[112:113], v[112:113], 0, v[144:145]
	v_lshl_add_u64 v[96:97], v[96:97], 0, v[144:145]
	v_lshl_add_u64 v[80:81], v[80:81], 0, v[144:145]
	v_lshl_add_u64 v[64:65], v[64:65], 0, v[144:145]
	v_lshl_add_u64 v[48:49], v[48:49], 0, v[144:145]
	v_lshl_add_u64 v[32:33], v[32:33], 0, v[144:145]
	v_lshl_add_u64 v[16:17], v[16:17], 0, v[144:145]
	v_cvt_pk_bf16_f32 v11, v0, v1
	s_andn2_b64 vcc, exec, s[6:7]
	s_mov_b64 s[6:7], -1
	global_store_dwordx4 v[156:157], v[120:123], off nt
	global_store_dwordx4 v[112:113], v[104:107], off nt
	global_store_dwordx4 v[96:97], v[88:91], off nt
	global_store_dwordx4 v[80:81], v[72:75], off nt
	global_store_dwordx4 v[64:65], v[56:59], off nt
	global_store_dwordx4 v[48:49], v[40:43], off nt
	global_store_dwordx4 v[32:33], v[24:27], off nt
	global_store_dwordx4 v[16:17], v[8:11], off nt
	s_cbranch_vccnz .LBB0_1307
	s_andn2_b64 vcc, exec, s[0:1]
	s_cbranch_vccnz .LBB0_1306
	s_barrier
	s_branch .LBB0_1306
